# in-projection phase: the odd converter workgroups run their weight-conversion shadow work before their GEMM units, so the two halves of the chip are out of step and epilogue store bursts fall into the
# baseline (speedup 1.0000x reference)
.LBB0_6:
	s_load_dwordx2 s[18:19], s[0:1], 0xc0
	s_lshl_b32 s2, s93, 3
	v_writelane_b32 v252, s2, 4
	s_load_dwordx16 s[60:75], s[0:1], 0x40
	v_mov_b32_e32 v203, 0x358637bd
	s_waitcnt lgkmcnt(0)
	s_lshl_b32 s33, s18, 3
	s_add_u32 s2, s8, 0x6204000
	s_addc_u32 s3, s9, 0
	v_writelane_b32 v252, s2, 5
	s_lshl_b32 s96, s18, 5
	v_mov_b32_e32 v204, 0x3c0881c4
	v_writelane_b32 v252, s3, 6
	v_writelane_b32 v252, s20, 7
	v_mov_b32_e32 v205, 0xbab64f3b
	v_mov_b32_e32 v206, 1
	v_writelane_b32 v252, s21, 8
	s_lshl_b32 s20, s93, 1
	s_cmpk_lt_i32 s20, 0x2180
	s_cselect_b64 s[2:3], -1, 0
	v_writelane_b32 v252, s2, 9
	v_mov_b32_e32 v215, 0x4000
	v_bfrev_b32_e32 v216, 0.5
	v_writelane_b32 v252, s3, 10
	s_add_u32 s2, s8, 0x16a94000
	s_addc_u32 s3, s9, 0
	s_add_u32 s46, s8, 0x4000
	v_writelane_b32 v252, s2, 11
	s_addc_u32 s47, s9, 0
	v_mov_b32_e32 v217, 0x3e000000
	v_writelane_b32 v252, s3, 12
	s_add_u32 s2, s8, 0x1304000
	s_addc_u32 s3, s9, 0
	v_writelane_b32 v252, s2, 13
	v_mov_b32_e32 v218, 0x4f
	v_mov_b32_e32 v219, 0x5f
	v_writelane_b32 v252, s3, 14
	s_add_u32 s2, s8, 0x804000
	s_addc_u32 s3, s9, 0
	v_writelane_b32 v252, s2, 15
	v_mov_b32_e32 v220, 0x6f
	v_mov_b32_e32 v221, 0xfffff500
	v_writelane_b32 v252, s3, 16
	s_add_u32 s2, s8, 0x604000
	s_addc_u32 s3, s9, 0
	s_lshl_b32 s48, s18, 1
	v_writelane_b32 v252, s2, 17
	s_add_u32 s44, s8, 0x16ac4000
	s_addc_u32 s45, s9, 0
	v_writelane_b32 v252, s3, 18
	s_lshl_b32 s2, s93, 9
	s_lshl_b32 s56, s18, 9
	v_writelane_b32 v252, s2, 19
	s_add_u32 s2, s8, 0xa304000
	s_addc_u32 s3, s9, 0
	v_writelane_b32 v252, s2, 20
	s_cmpk_lt_i32 s93, 0x100
	v_mov_b32_e32 v222, 0x7f800000
	v_writelane_b32 v252, s3, 21
	s_cselect_b64 s[2:3], -1, 0
	v_writelane_b32 v252, s2, 22
	v_not_b32_e32 v223, 63
	v_not_b32_e32 v224, 31
	v_writelane_b32 v252, s3, 23
	s_and_b32 s2, s93, 3
	v_writelane_b32 v252, s2, 24
	s_lshl_b32 s2, s93, 6
	s_and_b32 s2, s2, 0x3f00
	v_writelane_b32 v252, s2, 25
	s_ashr_i32 s2, s93, 31
	v_writelane_b32 v252, s2, 26
	s_lshr_b32 s2, s2, 29
	s_add_i32 s2, s93, s2
	s_ashr_i32 s21, s2, 3
	s_and_b32 s2, s2, -8
	s_sub_i32 s22, s93, s2
	s_lshl_b32 s3, s22, 5
	s_ashr_i32 s2, s18, 31
	s_add_u32 s12, s8, 0xc404000
	v_writelane_b32 v252, s2, 27
	s_addc_u32 s13, s9, 0
	v_writelane_b32 v252, s12, 28
	s_mul_hi_i32 s2, s93, 0x2aaaaaab
	v_mov_b32_e32 v225, 0x7fc00000
	v_writelane_b32 v252, s13, 29
	s_add_u32 s12, s8, 0x16acc000
	s_addc_u32 s13, s9, 0
	v_writelane_b32 v252, s12, 30
	s_movk_i32 s37, 0x4000
	s_mov_b32 s30, 0x18000
	v_writelane_b32 v252, s13, 31
	s_add_u32 s12, s8, 0x12da4000
	s_addc_u32 s13, s9, 0
	s_add_u32 s24, s8, 0x139d4000
	s_addc_u32 s25, s9, 0
	v_writelane_b32 v252, s12, 32
	s_add_u32 s94, s8, 0x15234000
	s_addc_u32 s95, s9, 0
	v_writelane_b32 v252, s13, 33
	s_lshr_b32 s12, s2, 31
	s_add_i32 s15, s2, s12
	s_mul_i32 s2, s15, 6
	s_sub_i32 s23, s93, s2
	s_lshl_b32 s16, s15, 8
	s_lshl_b32 s26, s23, 6
	s_add_i32 s2, s16, 0x100
	s_ashr_i32 s27, s26, 31
	s_cmpk_lt_i32 s93, 0x60
	s_cselect_b64 s[28:29], -1, 0
	v_writelane_b32 v252, s28, 34
	s_lshl_b32 s13, s15, 4
	s_addk_i32 s13, 0x4000
	v_writelane_b32 v252, s29, 35
	v_writelane_b32 v252, s13, 36
	s_sub_i32 s13, s18, s23
	s_add_i32 s13, s13, 5
	s_lshl_b64 s[28:29], s[26:27], 1
	v_writelane_b32 v252, s13, 37
	s_add_u32 s13, s8, s28
	v_writelane_b32 v252, s28, 38
	s_addc_u32 s17, s9, s29
	s_mul_i32 s12, s23, 0x208000
	v_writelane_b32 v252, s29, 39
	s_add_u32 s28, s13, 0xc404500
	s_addc_u32 s29, s17, 0
	v_writelane_b32 v252, s28, 40
	s_add_u32 s12, s8, s12
	s_mov_b32 s31, 0xc000
	v_writelane_b32 v252, s29, 41
	v_writelane_b32 v252, s26, 42
	s_mul_hi_i32 s13, s26, 0x8200
	s_addc_u32 s13, s9, s13
	s_add_u32 s12, s12, 0x12174000
	v_writelane_b32 v252, s27, 43
	s_addc_u32 s13, s13, 0
	v_writelane_b32 v252, s12, 44
	s_mov_b32 s36, 0x30000
	s_movk_i32 s57, 0x1700
	v_writelane_b32 v252, s13, 45
	s_ashr_i32 s12, s23, 31
	v_writelane_b32 v252, s12, 46
	s_cmpk_lt_i32 s93, 0x30c
	s_mul_i32 s12, s22, 0x61
	s_cselect_b64 s[26:27], -1, 0
	s_add_i32 s17, s12, 4
	v_writelane_b32 v252, s26, 47
	s_add_u32 s12, s8, 0x16ac8000
	s_addc_u32 s13, s9, 0
	v_writelane_b32 v252, s27, 48
	v_writelane_b32 v252, s12, 49
	s_movk_i32 s76, 0x104
	s_mov_b32 s77, 0x5c000
	v_writelane_b32 v252, s13, 50
	s_add_u32 s12, s8, 0x14604000
	s_addc_u32 s13, s9, 0
	v_writelane_b32 v252, s12, 51
	s_nop 1
	v_writelane_b32 v252, s13, 52
	s_mul_i32 s12, s18, -3
	s_addk_i32 s12, 0x30c
	s_cmp_eq_u32 s18, 0x100
	s_cselect_b32 s12, 48, s12
	s_cmp_gt_i32 s12, 0
	s_cselect_b64 s[26:27], -1, 0
	s_cmp_le_i32 s18, s12
	s_cselect_b64 s[28:29], -1, 0
	v_writelane_b32 v252, s28, 53
	s_cmp_lt_i32 s93, s12
	s_nop 0
	v_writelane_b32 v252, s29, 54
	s_cselect_b64 s[28:29], -1, 0
	s_sub_i32 s13, s93, s12
	v_writelane_b32 v252, s28, 55
	s_cmpk_lt_u32 s13, 0x2c0
	s_nop 0
	v_writelane_b32 v252, s29, 56
	s_cselect_b64 s[28:29], -1, 0
	v_writelane_b32 v252, s28, 57
	s_sub_i32 s13, s18, s12
	s_lshl_b32 s13, s13, 1
	v_writelane_b32 v252, s29, 58
	v_writelane_b32 v252, s13, 59
	s_cmp_gt_i32 s18, s12
	s_cselect_b64 s[12:13], -1, 0
	v_writelane_b32 v252, s26, 60
	s_and_b64 s[12:13], s[26:27], s[12:13]
	s_cmpk_lt_i32 s93, 0x2c0
	v_writelane_b32 v252, s27, 61
	v_writelane_b32 v252, s12, 62
	s_mov_b32 s28, 0x800000
	s_movk_i32 s29, 0x6000
	v_writelane_b32 v252, s13, 63
	s_cselect_b64 s[12:13], -1, 0
	v_writelane_b32 v253, s12, 0
	s_cmp_gt_i32 s11, 38
	s_nop 0
	v_writelane_b32 v253, s13, 1
	s_cselect_b64 s[12:13], -1, 0
	v_writelane_b32 v253, s12, 2
	s_nop 1
	v_writelane_b32 v253, s13, 3
	s_add_u32 s12, s8, 0x200
	s_addc_u32 s13, s9, 0
	v_writelane_b32 v253, s12, 4
	s_nop 1
	v_writelane_b32 v253, s13, 5
	s_add_u32 s12, s8, 0x1000
	s_addc_u32 s13, s9, 0
	v_writelane_b32 v253, s12, 6
	s_nop 1
	v_writelane_b32 v253, s13, 7
	s_add_u32 s12, s8, 0x1100
	s_addc_u32 s13, s9, 0
	v_writelane_b32 v253, s12, 8
	s_nop 1
	v_writelane_b32 v253, s13, 9
	s_add_u32 s12, s8, 0x1200
	s_addc_u32 s13, s9, 0
	v_writelane_b32 v253, s12, 10
	s_nop 1
	v_writelane_b32 v253, s13, 11
	s_add_u32 s12, s8, 0x1300
	s_addc_u32 s13, s9, 0
	v_writelane_b32 v253, s12, 12
	s_cmp_eq_u32 s14, 15
	s_nop 0
	v_writelane_b32 v253, s13, 13
	s_cselect_b64 s[12:13], -1, 0
	v_writelane_b32 v253, s12, 14
	s_cmp_eq_u32 s14, 14
	s_nop 0
	v_writelane_b32 v253, s13, 15
	s_cselect_b64 s[12:13], -1, 0
	v_writelane_b32 v253, s12, 16
	s_cmp_eq_u32 s14, 13
	s_nop 0
	v_writelane_b32 v253, s13, 17
	s_cselect_b64 s[12:13], -1, 0
	v_writelane_b32 v253, s12, 18
	s_cmp_eq_u32 s14, 12
	s_nop 0
	v_writelane_b32 v253, s13, 19
	s_cselect_b64 s[12:13], -1, 0
	v_writelane_b32 v253, s12, 20
	s_cmp_eq_u32 s14, 11
	s_nop 0
	v_writelane_b32 v253, s13, 21
	s_cselect_b64 s[12:13], -1, 0
	v_writelane_b32 v253, s12, 22
	s_cmp_eq_u32 s14, 10
	s_nop 0
	v_writelane_b32 v253, s13, 23
	s_cselect_b64 s[12:13], -1, 0
	v_writelane_b32 v253, s12, 24
	s_cmp_eq_u32 s14, 9
	s_nop 0
	v_writelane_b32 v253, s13, 25
	s_cselect_b64 s[12:13], -1, 0
	v_writelane_b32 v253, s12, 26
	s_cmp_eq_u32 s14, 8
	s_nop 0
	v_writelane_b32 v253, s13, 27
	s_cselect_b64 s[12:13], -1, 0
	v_writelane_b32 v253, s12, 28
	s_cmp_eq_u32 s14, 7
	s_nop 0
	v_writelane_b32 v253, s13, 29
	s_cselect_b64 s[12:13], -1, 0
	v_writelane_b32 v253, s12, 30
	s_cmp_eq_u32 s14, 6
	s_nop 0
	v_writelane_b32 v253, s13, 31
	s_cselect_b64 s[12:13], -1, 0
	v_writelane_b32 v253, s12, 32
	s_cmp_eq_u32 s14, 5
	s_nop 0
	v_writelane_b32 v253, s13, 33
	s_cselect_b64 s[12:13], -1, 0
	v_writelane_b32 v253, s12, 34
	s_cmp_eq_u32 s14, 4
	s_nop 0
	v_writelane_b32 v253, s13, 35
	s_cselect_b64 s[12:13], -1, 0
	v_writelane_b32 v253, s12, 36
	s_cmp_eq_u32 s14, 3
	s_nop 0
	v_writelane_b32 v253, s13, 37
	s_cselect_b64 s[12:13], -1, 0
	v_writelane_b32 v253, s12, 38
	s_cmp_eq_u32 s14, 2
	s_nop 0
	v_writelane_b32 v253, s13, 39
	s_cselect_b64 s[12:13], -1, 0
	v_writelane_b32 v253, s12, 40
	s_cmp_eq_u32 s14, 1
	s_nop 0
	v_writelane_b32 v253, s13, 41
	s_cselect_b64 s[12:13], -1, 0
	v_writelane_b32 v253, s12, 42
	s_cmp_eq_u32 s14, 0
	s_nop 0
	v_writelane_b32 v253, s13, 43
	s_cselect_b64 s[12:13], -1, 0
	v_writelane_b32 v253, s12, 44
	s_nop 1
	v_writelane_b32 v253, s13, 45
	s_lshl_b32 s12, s14, 8
	s_add_u32 s12, s8, s12
	s_addc_u32 s13, s9, 0
	s_add_u32 s26, s12, 0x1400
	s_addc_u32 s27, s13, 0
	v_writelane_b32 v253, s26, 46
	s_add_u32 s12, s12, 0x2400
	s_addc_u32 s13, s13, 0
	v_writelane_b32 v253, s27, 47
	v_writelane_b32 v253, s12, 48
	s_mov_b64 s[26:27], 0x400
	s_nop 0
	v_writelane_b32 v253, s13, 49
	s_add_u32 s12, s8, 0x3400
	s_addc_u32 s13, s9, 0
	v_writelane_b32 v253, s12, 50
	s_nop 1
	v_writelane_b32 v253, s13, 51
	s_add_u32 s12, s8, 0x3500
	s_addc_u32 s13, s9, 0
	v_writelane_b32 v253, s12, 52
	s_cmp_lt_i32 s22, 0
	s_nop 0
	v_writelane_b32 v253, s13, 53
	s_mul_i32 s12, s22, 33
	s_cselect_b32 s3, s12, s3
	s_add_i32 s3, s3, s21
	s_ashr_i32 s12, s3, 31
	s_lshr_b32 s12, s12, 27
	s_add_i32 s12, s3, s12
	s_and_b32 s13, s12, 0xffe0
	s_sub_i32 s3, s3, s13
	s_bfe_i32 s13, s3, 0x80000
	s_bfe_u32 s13, s13, 0x3000c
	s_add_i32 s13, s3, s13
	s_and_b32 s14, s13, 0xf8
	s_sub_i32 s3, s3, s14
	s_ashr_i32 s12, s12, 5
	s_lshl_b32 s12, s12, 3
	s_sext_i32_i8 s3, s3
	s_add_i32 s3, s12, s3
	v_writelane_b32 v253, s3, 54
	s_bfe_i32 s3, s13, 0x80000
	s_sext_i32_i16 s3, s3
	s_ashr_i32 s3, s3, 3
	v_writelane_b32 v253, s3, 55
	s_cmp_lt_i32 s22, 4
	s_mul_i32 s3, s22, 0x62
	s_cselect_b32 s3, s3, s17
	s_add_i32 s3, s3, s21
	s_mul_hi_i32 s12, s3, 0x2aaaaaab
	s_lshr_b32 s13, s12, 31
	s_ashr_i32 s12, s12, 4
	s_add_i32 s12, s12, s13
	s_mul_i32 s13, s12, 0x60
	s_lshl_b32 s12, s12, 3
	s_sub_i32 s13, s3, s13
	s_sub_i32 s3, 0x41, s12
	s_min_u32 s14, s3, 8
	v_cvt_f32_ubyte0_e32 v2, s14
	v_writelane_b32 v253, s22, 56
	v_cvt_f32_i32_e32 v1, s13
	v_rcp_iflag_f32_e32 v3, v2
	v_writelane_b32 v253, s21, 57
	s_bfe_i32 s3, s15, 0x10017
	v_writelane_b32 v253, s3, 58
	s_abs_i32 s3, s16
	v_writelane_b32 v253, s3, 59
	s_xor_b32 s3, s16, 0xffffff00
	s_max_i32 s3, s2, s3
	v_mul_f32_e32 v3, v1, v3
	v_writelane_b32 v253, s3, 60
	s_ashr_i32 s2, s2, 31
	v_trunc_f32_e32 v3, v3
	v_writelane_b32 v253, s2, 61
	s_ashr_i32 s2, s13, 30
	v_fma_f32 v1, -v3, v2, v1
	s_or_b32 s15, s2, 1
	v_cmp_ge_f32_e64 s[2:3], |v1|, v2
	s_and_b64 s[2:3], s[2:3], exec
	v_lshrrev_b32_e32 v1, 20, v0
	v_lshrrev_b32_e32 v0, 10, v0
	s_load_dword s3, s[0:1], 0xc8
	v_or_b32_e32 v0, v0, v1
	v_cvt_i32_f32_e32 v1, v3
	s_movk_i32 s2, 0x3ff
	v_and_or_b32 v0, v0, s2, v202
	s_mul_i32 s2, s19, s18
	s_waitcnt lgkmcnt(0)
	s_mul_i32 s49, s2, s3
	s_cselect_b32 s2, s15, 0
	v_readfirstlane_b32 s3, v1
	s_add_i32 s2, s3, s2
	s_mul_i32 s3, s2, s14
	s_sub_i32 s3, s13, s3
	s_sext_i32_i8 s3, s3
	s_add_i32 s3, s12, s3
	v_writelane_b32 v253, s3, 62
	s_sext_i32_i8 s2, s2
	v_writelane_b32 v253, s2, 63
	s_lshl_b32 s2, s18, 4
	v_writelane_b32 v254, s2, 0
	s_lshl_b32 s2, s93, 8
	s_ashr_i32 s97, s96, 31
	v_writelane_b32 v254, s2, 1
	s_lshl_b32 s2, s18, 8
	v_writelane_b32 v254, s2, 2
	s_lshl_b64 s[12:13], s[96:97], 12
	s_mul_i32 s2, s23, 0x744
	v_writelane_b32 v254, s12, 3
	s_add_u32 s2, s64, s2
	v_mov_b32_e32 v1, 0
	v_writelane_b32 v254, s13, 4
	v_writelane_b32 v254, s2, 5
	v_writelane_b32 v254, s23, 6
	v_writelane_b32 v254, s60, 7
	s_mul_hi_i32 s2, s23, 0x744
	s_addc_u32 s2, s65, s2
	v_writelane_b32 v254, s61, 8
	v_writelane_b32 v254, s62, 9
	v_writelane_b32 v254, s63, 10
	v_writelane_b32 v254, s64, 11
	v_writelane_b32 v254, s65, 12
	v_writelane_b32 v254, s66, 13
	v_writelane_b32 v254, s67, 14
	v_writelane_b32 v254, s68, 15
	v_writelane_b32 v254, s69, 16
	v_writelane_b32 v254, s70, 17
	v_writelane_b32 v254, s71, 18
	v_writelane_b32 v254, s72, 19
	v_writelane_b32 v254, s73, 20
	v_writelane_b32 v254, s74, 21
	v_writelane_b32 v254, s75, 22
	v_writelane_b32 v254, s2, 23
	s_mul_i32 s2, s18, 6
	s_add_i32 s2, s2, s20
	s_cmp_eq_u32 s18, 0x100
	s_cselect_b32 s3, 72, 0
	s_sub_i32 s2, s2, s3
	s_add_i32 s3, s2, 0xfffff9e8
	v_writelane_b32 v254, s3, 24
	s_addk_i32 s2, 0xfdc8
	v_writelane_b32 v254, s2, 25
	s_mul_i32 s2, s18, 24
	v_writelane_b32 v254, s2, 26
	s_add_i32 s2, s96, 0xffffe7a0
	s_cmp_eq_u32 s18, 0x100
	s_cselect_b32 s3, 0x120, 0
	s_sub_i32 s2, s2, s3
	v_writelane_b32 v254, s2, 27
	s_add_i32 s2, s56, 0xfffe7a00
	s_cmp_eq_u32 s18, 0x100
	s_cselect_b32 s3, 0x1200, 0
	s_sub_i32 s2, s2, s3
	v_writelane_b32 v254, s2, 28
	v_writelane_b32 v254, s20, 29
	s_add_i32 s2, s20, 0x3e0
	v_writelane_b32 v254, s2, 30
	s_lshl_b32 s2, s18, 7
	v_writelane_b32 v254, s2, 31
	s_add_i32 s2, 0, 0x820
	v_writelane_b32 v254, s2, 32
	s_add_i32 s2, 0, 0x5140
	v_writelane_b32 v254, s2, 33
	s_add_i32 s2, 0, 0x20800
	v_writelane_b32 v254, s2, 34
	s_add_i32 s2, 0, 0x201b0
	v_writelane_b32 v254, s2, 35
	s_add_i32 s2, 0, 0x21000
	v_writelane_b32 v254, s2, 36
	s_add_i32 s2, 0, 0x21004
	v_writelane_b32 v254, s2, 37
	s_mov_b32 s3, 0
	s_load_dwordx16 s[60:75], s[0:1], 0x0
	v_writelane_b32 v254, s2, 38
	s_mov_b32 s0, s96
	v_mbcnt_lo_u32_b32 v2, -1, 0
	v_writelane_b32 v254, s3, 39
	v_cmp_eq_u32_e64 s[2:3], 0, v0
	v_mbcnt_hi_u32_b32 v207, -1, v2
	v_and_b32_e32 v2, 64, v207
	v_writelane_b32 v254, s2, 40
	v_add_u32_e32 v208, 64, v2
	v_xor_b32_e32 v209, 32, v207
	v_writelane_b32 v254, s3, 41
	s_waitcnt lgkmcnt(0)
	v_writelane_b32 v254, s60, 42
	v_xor_b32_e32 v210, 16, v207
	v_xor_b32_e32 v211, 8, v207
	v_writelane_b32 v254, s61, 43
	v_writelane_b32 v254, s62, 44
	v_writelane_b32 v254, s63, 45
	v_writelane_b32 v254, s64, 46
	v_writelane_b32 v254, s65, 47
	v_writelane_b32 v254, s66, 48
	v_writelane_b32 v254, s67, 49
	v_writelane_b32 v254, s68, 50
	v_writelane_b32 v254, s69, 51
	v_writelane_b32 v254, s70, 52
	v_writelane_b32 v254, s71, 53
	v_writelane_b32 v254, s72, 54
	v_writelane_b32 v254, s73, 55
	v_writelane_b32 v254, s74, 56
	v_writelane_b32 v254, s75, 57
	v_writelane_b32 v254, s93, 58
	v_writelane_b32 v254, s84, 59
	v_xor_b32_e32 v212, 4, v207
	v_xor_b32_e32 v213, 2, v207
	v_writelane_b32 v255, s89, 0
	v_writelane_b32 v255, s90, 1
	v_writelane_b32 v255, s91, 2
	v_writelane_b32 v255, s0, 3
	v_writelane_b32 v254, s85, 60
	v_writelane_b32 v254, s86, 61
	v_writelane_b32 v255, s1, 4
	v_writelane_b32 v255, s46, 5
	v_writelane_b32 v254, s87, 62
	v_xor_b32_e32 v214, 1, v207
	v_writelane_b32 v255, s47, 6
	v_writelane_b32 v255, s48, 7
	v_writelane_b32 v255, s44, 8
	v_mov_b32_e32 v238, v1
	v_mov_b32_e32 v239, v1
	v_writelane_b32 v255, s45, 9
	v_writelane_b32 v255, s49, 10
	v_mov_b32_e32 v240, v1
	v_mov_b32_e32 v241, v1
	s_mov_b64 s[20:21], 0x80
	v_writelane_b32 v254, s88, 63
	v_writelane_b32 v255, s56, 11
	s_mov_b32 s2, 0
	s_nop 0
	v_writelane_b32 v255, s2, 22
	s_branch .LBB0_10

.Lcf_top:
	v_readlane_b32 s2, v252, 47
	v_readlane_b32 s3, v252, 48
	v_mov_b32_e32 v10, v202
	s_andn2_b64 vcc, exec, s[2:3]
	v_cndmask_b32_e64 v0, 0, 1, s[2:3]
	v_cmp_ne_u32_e64 s[0:1], 1, v0
	v_readfirstlane_b32 s22, v10
	s_cbranch_vccnz .LBB0_354
	v_readlane_b32 s2, v253, 63
	s_mov_b32 s14, s2
	v_readlane_b32 s42, v253, 62
.LBB0_354:
	v_readlane_b32 s2, v255, 22
	s_cmp_eq_u32 s2, 0
	s_cbranch_scc0 .Lcf_gemm
	v_readlane_b32 s2, v252, 2
	s_cmp_eq_u32 s2, 0x100
	s_cbranch_scc0 .Lcf_gemm
	s_and_b64 vcc, exec, s[50:51]
	s_cbranch_vccz .Lcf_gemm
	v_readlane_b32 s2, v254, 58
	s_cmp_lt_u32 s2, 48
	s_cbranch_scc1 .Lcf_gemm
	s_bitcmp1_b32 s2, 0
	s_cbranch_scc0 .Lcf_gemm
	s_mov_b32 s2, 1
	s_nop 0
	v_writelane_b32 v255, s2, 22
	s_branch .LBB0_482

.LBB0_482:
	v_readlane_b32 s2, v255, 22
	s_cmp_eq_u32 s2, 2
	s_cbranch_scc0 .Lcf_conv
	s_mov_b32 s2, 0
	s_nop 0
	v_writelane_b32 v255, s2, 22
	s_branch .LBB0_521

.LBB0_522:
	v_readlane_b32 s2, v255, 22
	s_cmp_eq_u32 s2, 1
	s_cbranch_scc0 .Lcf_end
	s_mov_b32 s2, 2
	s_nop 0
	v_writelane_b32 v255, s2, 22
	v_readlane_b32 s62, v255, 12
	v_readlane_b32 s63, v255, 13
	s_branch .Lcf_top
